# attention QK: K-fragment LDS reads issued 3-4 deep behind counted lgkmcnt waits using the idle PV fragment registers
# speedup vs baseline: 1.0094x; 1.0056x over previous
.LBB0_710:
	s_cmp_gt_i32 s50, s29
	s_cbranch_scc1 .LBB0_724
	s_bitcmp1_b32 s50, 0
	s_cselect_b32 s0, 0x11800, 0
	s_add_i32 s61, s0, 0
	s_add_i32 s0, s61, s69
	v_add_u32_e32 v1, s0, v210
	v_add_u32_e32 v229, v1, v225
	ds_read_b128 v[176:179], v229
	ds_read_b128 v[230:233], v229 offset:64
	ds_read_b128 v[234:237], v229 offset:128
	ds_read_b128 v[238:241], v229 offset:192
	v_xor_b32_e32 v180, 0x80000000, v228
	v_xor_b32_e32 v172, 0x80000000, v227
	v_mov_b32_e32 v181, v180
	v_mov_b32_e32 v182, v180
	v_mov_b32_e32 v183, v180
	v_mov_b32_e32 v173, v172
	v_mov_b32_e32 v174, v172
	v_mov_b32_e32 v175, v172
	s_waitcnt lgkmcnt(3)
	v_mfma_f32_16x16x32_bf16 v[184:187], v[176:179], v[100:103], v[180:183]
	v_mfma_f32_16x16x32_bf16 v[176:179], v[176:179], v[116:119], v[172:175]
	s_waitcnt lgkmcnt(2)
	v_mfma_f32_16x16x32_bf16 v[184:187], v[230:233], v[104:107], v[184:187]
	v_mfma_f32_16x16x32_bf16 v[176:179], v[230:233], v[120:123], v[176:179]
	ds_read_b128 v[230:233], v229 offset:4352
	s_waitcnt lgkmcnt(2)
	v_mfma_f32_16x16x32_bf16 v[184:187], v[234:237], v[108:111], v[184:187]
	v_mfma_f32_16x16x32_bf16 v[176:179], v[234:237], v[124:127], v[176:179]
	ds_read_b128 v[234:237], v229 offset:4416
	s_waitcnt lgkmcnt(2)
	v_mfma_f32_16x16x32_bf16 v[184:187], v[238:241], v[112:115], v[184:187]
	v_mfma_f32_16x16x32_bf16 v[176:179], v[238:241], v[128:131], v[176:179]
	ds_read_b128 v[238:241], v229 offset:4480
	s_waitcnt lgkmcnt(2)
	v_mfma_f32_16x16x32_bf16 v[188:191], v[230:233], v[100:103], v[180:183]
	v_mfma_f32_16x16x32_bf16 v[180:183], v[230:233], v[116:119], v[172:175]
	ds_read_b128 v[230:233], v229 offset:4544
	s_waitcnt lgkmcnt(2)
	v_mfma_f32_16x16x32_bf16 v[188:191], v[234:237], v[104:107], v[188:191]
	v_mfma_f32_16x16x32_bf16 v[180:183], v[234:237], v[120:123], v[180:183]
	s_waitcnt lgkmcnt(1)
	v_mfma_f32_16x16x32_bf16 v[188:191], v[238:241], v[108:111], v[188:191]
	v_mfma_f32_16x16x32_bf16 v[180:183], v[238:241], v[124:127], v[180:183]
	s_waitcnt lgkmcnt(0)
	v_mfma_f32_16x16x32_bf16 v[188:191], v[230:233], v[112:115], v[188:191]
	v_mfma_f32_16x16x32_bf16 v[180:183], v[230:233], v[128:131], v[180:183]
	v_max_f32_e32 v1, v185, v185
	v_max_f32_e32 v2, v184, v184
	v_max_f32_e32 v1, v2, v1
	v_max_f32_e32 v2, v187, v187
	v_max_f32_e32 v3, v186, v186
	v_max_f32_e32 v2, v3, v2
	s_nop 0
	v_max_f32_e32 v3, v191, v191
	v_max_f32_e32 v173, v190, v190
	s_cmp_eq_u32 s50, 0
	v_max_f32_e32 v3, v173, v3
	s_cselect_b64 s[0:1], -1, 0
	s_cmp_lg_u32 s50, 0
	v_max3_f32 v3, v188, v189, v3
	s_mov_b64 s[2:3], s[0:1]
	s_cselect_b64 s[78:79], -1, 0
	v_max3_f32 v1, v1, v2, v3
	s_and_b64 vcc, exec, s[0:1]
	s_mov_b64 s[50:51], s[0:1]
	s_cbranch_vccnz .LBB0_713
	v_cmp_lt_f32_e32 vcc, s77, v1
	s_cmp_lg_u64 vcc, 0
	s_cselect_b64 s[50:51], -1, 0

.LBB0_719:
	v_add_u32_e32 v1, s61, v226
	s_mov_b32 s0, 0x8800
	v_add3_u32 v188, v1, v225, s0
	v_exp_f32_e32 v1, v176
	v_exp_f32_e32 v2, v177
	v_exp_f32_e32 v3, v178
	v_exp_f32_e32 v177, v179
	v_cvt_pk_bf16_f32 v176, v1, v2
	v_cvt_pk_bf16_f32 v177, v3, v177
	v_mov_b32_e32 v1, v0
	v_mov_b32_e32 v2, v0
	v_mov_b32_e32 v3, v0
	v_exp_f32_e32 v178, v180
	v_exp_f32_e32 v179, v181
	v_exp_f32_e32 v180, v182
	v_exp_f32_e32 v181, v183
	v_cvt_pk_bf16_f32 v178, v178, v179
	v_cvt_pk_bf16_f32 v179, v180, v181
	v_mov_b32_e32 v173, v172
	v_mfma_f32_16x16x32_bf16 v[164:167], v[0:3], v[176:179], v[164:167]
	v_mov_b32_e32 v174, v172
	v_mov_b32_e32 v175, v172
	ds_read_b128 v[180:183], v188 offset:0
	ds_read_b128 v[230:233], v188 offset:0x900
	ds_read_b128 v[234:237], v188 offset:0x1200
	ds_read_b128 v[238:241], v188 offset:0x1b00
	s_nop 0
	s_waitcnt lgkmcnt(2)
	s_nop 0
	v_mfma_f32_16x16x32_bf16 v[160:163], v[180:183], v[184:187], v[160:163]
	v_mfma_f32_16x16x32_bf16 v[152:155], v[230:233], v[184:187], v[152:155]
	v_mfma_f32_16x16x32_bf16 v[156:159], v[180:183], v[176:179], v[156:159]
	ds_read_b128 v[180:183], v188 offset:0x2400
	v_mfma_f32_16x16x32_bf16 v[148:151], v[230:233], v[176:179], v[148:151]
	ds_read_b128 v[230:233], v188 offset:0x2d00
	s_waitcnt lgkmcnt(2)
	s_nop 0
	v_mfma_f32_16x16x32_bf16 v[144:147], v[234:237], v[184:187], v[144:147]
	v_mfma_f32_16x16x32_bf16 v[136:139], v[238:241], v[184:187], v[136:139]
	v_mfma_f32_16x16x32_bf16 v[140:143], v[234:237], v[176:179], v[140:143]
	ds_read_b128 v[234:237], v188 offset:0x3600
	v_mfma_f32_16x16x32_bf16 v[132:135], v[238:241], v[176:179], v[132:135]
	ds_read_b128 v[238:241], v188 offset:0x3f00
	s_waitcnt lgkmcnt(2)
	s_nop 0
	v_mfma_f32_16x16x32_bf16 v[96:99], v[180:183], v[184:187], v[96:99]
	v_mfma_f32_16x16x32_bf16 v[88:91], v[230:233], v[184:187], v[88:91]
	v_mfma_f32_16x16x32_bf16 v[92:95], v[180:183], v[176:179], v[92:95]
	ds_read_b128 v[180:183], v188 offset:0x4800
	v_mfma_f32_16x16x32_bf16 v[84:87], v[230:233], v[176:179], v[84:87]
	ds_read_b128 v[230:233], v188 offset:0x5100
	s_waitcnt lgkmcnt(2)
	s_nop 0
	v_mfma_f32_16x16x32_bf16 v[80:83], v[234:237], v[184:187], v[80:83]
	v_mfma_f32_16x16x32_bf16 v[72:75], v[238:241], v[184:187], v[72:75]
	v_mfma_f32_16x16x32_bf16 v[76:79], v[234:237], v[176:179], v[76:79]
	ds_read_b128 v[234:237], v188 offset:0x5a00
	v_mfma_f32_16x16x32_bf16 v[68:71], v[238:241], v[176:179], v[68:71]
	ds_read_b128 v[238:241], v188 offset:0x6300
	s_waitcnt lgkmcnt(2)
	s_nop 0
	v_mfma_f32_16x16x32_bf16 v[64:67], v[180:183], v[184:187], v[64:67]
	v_mfma_f32_16x16x32_bf16 v[56:59], v[230:233], v[184:187], v[56:59]
	v_mfma_f32_16x16x32_bf16 v[60:63], v[180:183], v[176:179], v[60:63]
	ds_read_b128 v[180:183], v188 offset:0x6c00
	v_mfma_f32_16x16x32_bf16 v[52:55], v[230:233], v[176:179], v[52:55]
	ds_read_b128 v[230:233], v188 offset:0x7500
	s_waitcnt lgkmcnt(2)
	s_nop 0
	v_mfma_f32_16x16x32_bf16 v[48:51], v[234:237], v[184:187], v[48:51]
	v_mfma_f32_16x16x32_bf16 v[40:43], v[238:241], v[184:187], v[40:43]
	v_mfma_f32_16x16x32_bf16 v[44:47], v[234:237], v[176:179], v[44:47]
	ds_read_b128 v[234:237], v188 offset:0x7e00
	v_mfma_f32_16x16x32_bf16 v[36:39], v[238:241], v[176:179], v[36:39]
	ds_read_b128 v[238:241], v188 offset:0x8700
	s_waitcnt lgkmcnt(2)
	s_nop 0
	v_mfma_f32_16x16x32_bf16 v[32:35], v[180:183], v[184:187], v[32:35]
	s_waitcnt lgkmcnt(0)
	v_mfma_f32_16x16x32_bf16 v[24:27], v[230:233], v[184:187], v[24:27]
	v_mfma_f32_16x16x32_bf16 v[28:31], v[180:183], v[176:179], v[28:31]
	v_mfma_f32_16x16x32_bf16 v[20:23], v[230:233], v[176:179], v[20:23]
	v_mfma_f32_16x16x32_bf16 v[16:19], v[234:237], v[184:187], v[16:19]
	v_mfma_f32_16x16x32_bf16 v[8:11], v[238:241], v[184:187], v[8:11]
	v_mfma_f32_16x16x32_bf16 v[12:15], v[234:237], v[176:179], v[12:15]
	v_mfma_f32_16x16x32_bf16 v[4:7], v[238:241], v[176:179], v[4:7]
	ds_read_b128 v[176:179], v229 offset:8704
	ds_read_b128 v[230:233], v229 offset:8768
	ds_read_b128 v[234:237], v229 offset:8832
	ds_read_b128 v[238:241], v229 offset:8896
	v_xor_b32_e32 v184, 0x80000000, v228
	v_mov_b32_e32 v185, v184
	v_mov_b32_e32 v186, v184
	v_mov_b32_e32 v187, v184
	s_waitcnt lgkmcnt(3)
	s_nop 0
	v_mfma_f32_16x16x32_bf16 v[180:183], v[176:179], v[100:103], v[184:187]
	v_mfma_f32_16x16x32_bf16 v[176:179], v[176:179], v[116:119], v[172:175]
	s_waitcnt lgkmcnt(2)
	v_mfma_f32_16x16x32_bf16 v[180:183], v[230:233], v[104:107], v[180:183]
	v_mfma_f32_16x16x32_bf16 v[176:179], v[230:233], v[120:123], v[176:179]
	ds_read_b128 v[230:233], v229 offset:13056
	s_waitcnt lgkmcnt(2)
	v_mfma_f32_16x16x32_bf16 v[180:183], v[234:237], v[108:111], v[180:183]
	v_mfma_f32_16x16x32_bf16 v[176:179], v[234:237], v[124:127], v[176:179]
	ds_read_b128 v[234:237], v229 offset:13120
	s_waitcnt lgkmcnt(2)
	v_mfma_f32_16x16x32_bf16 v[180:183], v[238:241], v[112:115], v[180:183]
	v_mfma_f32_16x16x32_bf16 v[176:179], v[238:241], v[128:131], v[176:179]
	ds_read_b128 v[238:241], v229 offset:13184
	s_waitcnt lgkmcnt(2)
	v_mfma_f32_16x16x32_bf16 v[184:187], v[230:233], v[100:103], v[184:187]
	v_mfma_f32_16x16x32_bf16 v[172:175], v[230:233], v[116:119], v[172:175]
	ds_read_b128 v[230:233], v229 offset:13248
	s_waitcnt lgkmcnt(2)
	v_mfma_f32_16x16x32_bf16 v[184:187], v[234:237], v[104:107], v[184:187]
	v_mfma_f32_16x16x32_bf16 v[172:175], v[234:237], v[120:123], v[172:175]
	s_waitcnt lgkmcnt(1)
	v_mfma_f32_16x16x32_bf16 v[184:187], v[238:241], v[108:111], v[184:187]
	v_mfma_f32_16x16x32_bf16 v[172:175], v[238:241], v[124:127], v[172:175]
	s_waitcnt lgkmcnt(0)
	v_mfma_f32_16x16x32_bf16 v[184:187], v[230:233], v[112:115], v[184:187]
	v_mfma_f32_16x16x32_bf16 v[172:175], v[230:233], v[128:131], v[172:175]
	v_max_f32_e32 v189, v181, v181
	v_max_f32_e32 v190, v180, v180
	v_max_f32_e32 v189, v190, v189
	v_max_f32_e32 v190, v183, v183
	v_max_f32_e32 v191, v182, v182
	v_max_f32_e32 v190, v191, v190
	s_nop 0
	v_max_f32_e32 v191, v187, v187
	v_max_f32_e32 v212, v186, v186
	v_max_f32_e32 v191, v212, v191
	v_max3_f32 v191, v184, v185, v191
	v_max3_f32 v189, v189, v190, v191
	v_cmp_lt_f32_e32 vcc, s77, v189
	s_cbranch_vccz .LBB0_721
	v_mov_b32_e32 v190, v189
	s_nop 1
	v_permlane16_swap_b32_e32 v189, v190
	v_max_f32_e32 v190, v190, v190
	v_max_f32_e32 v189, v189, v189
	v_max_f32_e32 v189, v189, v190
	v_mov_b32_e32 v190, v189
	s_nop 1
	v_permlane32_swap_b32_e32 v189, v190
	v_max3_f32 v189, v189, v190, 0
	v_exp_f32_e64 v190, -v189
	v_add_f32_e32 v228, v228, v189
	v_sub_f32_e32 v180, v180, v189
	v_sub_f32_e32 v181, v181, v189
	v_pk_mul_f32 v[170:171], v[170:171], v[190:191] op_sel_hi:[1,0]
	v_pk_mul_f32 v[168:169], v[168:169], v[190:191] op_sel_hi:[1,0]
	v_pk_mul_f32 v[162:163], v[162:163], v[190:191] op_sel_hi:[1,0]
	v_pk_mul_f32 v[160:161], v[160:161], v[190:191] op_sel_hi:[1,0]
	v_pk_mul_f32 v[154:155], v[154:155], v[190:191] op_sel_hi:[1,0]
	v_pk_mul_f32 v[152:153], v[152:153], v[190:191] op_sel_hi:[1,0]
	v_pk_mul_f32 v[146:147], v[146:147], v[190:191] op_sel_hi:[1,0]
	v_pk_mul_f32 v[144:145], v[144:145], v[190:191] op_sel_hi:[1,0]
	v_pk_mul_f32 v[138:139], v[138:139], v[190:191] op_sel_hi:[1,0]
	v_pk_mul_f32 v[136:137], v[136:137], v[190:191] op_sel_hi:[1,0]
	v_pk_mul_f32 v[98:99], v[98:99], v[190:191] op_sel_hi:[1,0]
	v_pk_mul_f32 v[96:97], v[96:97], v[190:191] op_sel_hi:[1,0]
	v_pk_mul_f32 v[90:91], v[90:91], v[190:191] op_sel_hi:[1,0]
	v_pk_mul_f32 v[88:89], v[88:89], v[190:191] op_sel_hi:[1,0]
	v_pk_mul_f32 v[82:83], v[82:83], v[190:191] op_sel_hi:[1,0]
	v_pk_mul_f32 v[80:81], v[80:81], v[190:191] op_sel_hi:[1,0]
	v_pk_mul_f32 v[74:75], v[74:75], v[190:191] op_sel_hi:[1,0]
	v_pk_mul_f32 v[72:73], v[72:73], v[190:191] op_sel_hi:[1,0]
	v_pk_mul_f32 v[66:67], v[66:67], v[190:191] op_sel_hi:[1,0]
	v_pk_mul_f32 v[64:65], v[64:65], v[190:191] op_sel_hi:[1,0]
	v_pk_mul_f32 v[58:59], v[58:59], v[190:191] op_sel_hi:[1,0]
	v_pk_mul_f32 v[56:57], v[56:57], v[190:191] op_sel_hi:[1,0]
	v_pk_mul_f32 v[50:51], v[50:51], v[190:191] op_sel_hi:[1,0]
	v_pk_mul_f32 v[48:49], v[48:49], v[190:191] op_sel_hi:[1,0]
	v_pk_mul_f32 v[42:43], v[42:43], v[190:191] op_sel_hi:[1,0]
	v_pk_mul_f32 v[40:41], v[40:41], v[190:191] op_sel_hi:[1,0]
	v_pk_mul_f32 v[34:35], v[34:35], v[190:191] op_sel_hi:[1,0]
	v_pk_mul_f32 v[32:33], v[32:33], v[190:191] op_sel_hi:[1,0]
	v_pk_mul_f32 v[26:27], v[26:27], v[190:191] op_sel_hi:[1,0]
	v_pk_mul_f32 v[24:25], v[24:25], v[190:191] op_sel_hi:[1,0]
	v_pk_mul_f32 v[18:19], v[18:19], v[190:191] op_sel_hi:[1,0]
	v_pk_mul_f32 v[16:17], v[16:17], v[190:191] op_sel_hi:[1,0]
	v_pk_mul_f32 v[10:11], v[10:11], v[190:191] op_sel_hi:[1,0]
	v_pk_mul_f32 v[8:9], v[8:9], v[190:191] op_sel_hi:[1,0]
	v_sub_f32_e32 v182, v182, v189
	v_sub_f32_e32 v183, v183, v189
	v_sub_f32_e32 v184, v184, v189
	v_sub_f32_e32 v185, v185, v189
	v_sub_f32_e32 v186, v186, v189
	v_sub_f32_e32 v187, v187, v189
